# L2 warm-up loads for S5 state and EX rows at lru_out start; gla->ssd boundary barrier moved below the ssd dt softplus/cumsum compute
# baseline (speedup 1.0000x reference)
.LBB0_388:
	s_and_b64 vcc, exec, s[0:1]
	s_cbranch_vccz .LBB0_392
	s_waitcnt lgkmcnt(0)
	v_mov_b32_e32 v1, v0
	s_ashr_i32 s29, s28, 31
	s_lshl_b32 s88, s28, 6
	v_readlane_b32 s36, v251, 55
	v_readlane_b32 s37, v251, 56
	v_lshlrev_b32_e32 v194, 3, v0
	v_and_b32_e32 v194, 0x1f8, v194
	v_lshlrev_b32_e32 v194, 1, v194
	v_mov_b32_e32 v195, 0
	v_ashrrev_i32_e32 v196, 6, v0
	v_add_u32_e32 v196, s88, v196
	s_movk_i32 s38, 0x2800
	v_mov_b64_e32 v[198:199], s[36:37]
	s_mov_b64 s[44:45], 0x14000
	v_mad_i64_i32 v[200:201], s[40:41], v196, s38, v[198:199]
	v_readlane_b32 s46, v250, 35
	v_readlane_b32 s47, v250, 36
	v_readlane_b32 s52, v250, 47
	v_readlane_b32 s53, v250, 48
	s_lshl_b64 s[48:49], s[28:29], 14
	v_lshlrev_b32_e32 v203, 5, v0
	s_add_u32 s46, s46, s48
	s_addc_u32 s47, s47, s49
	s_lshl_b32 s48, s88, 7
	v_and_b32_e32 v204, 63, v0
	s_add_u32 s52, s52, s48
	s_addc_u32 s53, s53, 0
	v_lshlrev_b32_e32 v204, 7, v204
	global_load_dword v202, v203, s[46:47]
	global_load_dword v205, v204, s[52:53]
	v_lshl_add_u64 v[200:201], v[200:201], 0, v[194:195]
	global_load_dwordx4 v[162:165], v[200:201], off offset:3584
	v_lshl_add_u64 v[200:201], v[200:201], 0, s[44:45]
	global_load_dwordx4 v[166:169], v[200:201], off offset:3584
	v_lshl_add_u64 v[200:201], v[200:201], 0, s[44:45]
	global_load_dwordx4 v[170:173], v[200:201], off offset:3584
	v_lshl_add_u64 v[200:201], v[200:201], 0, s[44:45]
	global_load_dwordx4 v[174:177], v[200:201], off offset:3584
	v_lshl_add_u64 v[200:201], v[200:201], 0, s[44:45]
	global_load_dwordx4 v[178:181], v[200:201], off offset:3584
	v_lshl_add_u64 v[200:201], v[200:201], 0, s[44:45]
	global_load_dwordx4 v[182:185], v[200:201], off offset:3584
	v_lshl_add_u64 v[200:201], v[200:201], 0, s[44:45]
	global_load_dwordx4 v[186:189], v[200:201], off offset:3584
	v_lshl_add_u64 v[200:201], v[200:201], 0, s[44:45]
	global_load_dwordx4 v[190:193], v[200:201], off offset:3584
	s_lshl_b64 s[0:1], s[28:29], 11
	v_readlane_b32 s4, v250, 33
	v_lshlrev_b32_e32 v6, 3, v1
	s_add_u32 s0, s4, s0
	v_readlane_b32 s4, v250, 34
	v_and_b32_e32 v11, 0x1f8, v6
	s_addc_u32 s1, s4, s1
	v_lshlrev_b32_e32 v138, 2, v11
	s_waitcnt lgkmcnt(0)
	global_load_dwordx4 v[6:9], v138, s[0:1] offset:16
	global_load_dwordx4 v[14:17], v138, s[0:1]
	v_ashrrev_i32_e32 v1, 3, v1
	v_readlane_b32 s0, v250, 41
	v_and_b32_e32 v1, -8, v1
	v_readlane_b32 s1, v250, 42
	v_add_u32_e32 v10, s88, v1
	s_movk_i32 s4, 0x2800
	v_lshl_add_u64 v[12:13], s[0:1], 0, v[138:139]
	v_readlane_b32 s0, v251, 55
	v_lshlrev_b32_e32 v138, 1, v11
	v_readlane_b32 s1, v251, 56
	v_ashrrev_i32_e32 v11, 31, v10
	v_lshlrev_b64 v[20:21], 11, v[10:11]
	v_lshl_add_u64 v[18:19], s[0:1], 0, v[138:139]
	v_lshl_add_u64 v[20:21], v[12:13], 0, v[20:21]
	v_mad_i64_i32 v[120:121], s[0:1], v10, s4, v[18:19]
	global_load_dwordx4 v[98:101], v[20:21], off offset:16
	global_load_dwordx4 v[124:127], v[20:21], off
	global_load_dwordx4 v[102:105], v[120:121], off
	v_or_b32_e32 v20, 1, v10
	v_ashrrev_i32_e32 v21, 31, v20
	v_lshlrev_b64 v[22:23], 11, v[20:21]
	v_lshl_add_u64 v[22:23], v[12:13], 0, v[22:23]
	v_mad_i64_i32 v[118:119], s[0:1], v20, s4, v[18:19]
	global_load_dwordx4 v[86:89], v[22:23], off offset:16
	global_load_dwordx4 v[94:97], v[22:23], off
	global_load_dwordx4 v[90:93], v[118:119], off
	v_or_b32_e32 v20, 2, v10
	v_ashrrev_i32_e32 v21, 31, v20
	v_lshlrev_b64 v[22:23], 11, v[20:21]
	v_lshl_add_u64 v[22:23], v[12:13], 0, v[22:23]
	v_mad_i64_i32 v[116:117], s[0:1], v20, s4, v[18:19]
	global_load_dwordx4 v[74:77], v[22:23], off offset:16
	global_load_dwordx4 v[82:85], v[22:23], off
	global_load_dwordx4 v[78:81], v[116:117], off
	v_or_b32_e32 v20, 3, v10
	v_ashrrev_i32_e32 v21, 31, v20
	v_lshlrev_b64 v[22:23], 11, v[20:21]
	v_mad_i64_i32 v[114:115], s[0:1], v20, s4, v[18:19]
	v_or_b32_e32 v20, 4, v10
	v_lshl_add_u64 v[22:23], v[12:13], 0, v[22:23]
	v_ashrrev_i32_e32 v21, 31, v20
	global_load_dwordx4 v[62:65], v[22:23], off offset:16
	global_load_dwordx4 v[70:73], v[22:23], off
	v_lshlrev_b64 v[22:23], 11, v[20:21]
	v_mad_i64_i32 v[112:113], s[0:1], v20, s4, v[18:19]
	v_or_b32_e32 v20, 5, v10
	v_lshl_add_u64 v[22:23], v[12:13], 0, v[22:23]
	v_ashrrev_i32_e32 v21, 31, v20
	global_load_dwordx4 v[66:69], v[114:115], off
	global_load_dwordx4 v[50:53], v[22:23], off offset:16
	global_load_dwordx4 v[58:61], v[22:23], off
	v_lshlrev_b64 v[22:23], 11, v[20:21]
	v_mad_i64_i32 v[110:111], s[0:1], v20, s4, v[18:19]
	v_or_b32_e32 v20, 6, v10
	v_lshl_add_u64 v[22:23], v[12:13], 0, v[22:23]
	v_ashrrev_i32_e32 v21, 31, v20
	global_load_dwordx4 v[54:57], v[112:113], off
	global_load_dwordx4 v[38:41], v[22:23], off offset:16
	global_load_dwordx4 v[46:49], v[22:23], off
	v_lshlrev_b64 v[22:23], 11, v[20:21]
	v_mad_i64_i32 v[108:109], s[0:1], v20, s4, v[18:19]
	v_or_b32_e32 v20, 7, v10
	v_ashrrev_i32_e32 v21, 31, v20
	v_lshl_add_u64 v[22:23], v[12:13], 0, v[22:23]
	v_lshlrev_b64 v[10:11], 11, v[20:21]
	global_load_dwordx4 v[42:45], v[110:111], off
	global_load_dwordx4 v[26:29], v[22:23], off offset:16
	global_load_dwordx4 v[34:37], v[22:23], off
	v_lshl_add_u64 v[22:23], v[12:13], 0, v[10:11]
	v_mad_i64_i32 v[106:107], s[0:1], v20, s4, v[18:19]
	global_load_dwordx4 v[30:33], v[108:109], off
	global_load_dwordx4 v[10:13], v[22:23], off offset:16
	s_nop 0
	global_load_dwordx4 v[22:25], v[22:23], off
	s_waitcnt vmcnt(0)
	v_and_b32_e32 v135, 0xffff0000, v126
	v_lshlrev_b32_e32 v122, 16, v102
	v_mul_f32_e32 v1, 0xbfb8aa3b, v122
	v_exp_f32_e32 v1, v1
	v_and_b32_e32 v130, 0xffff0000, v102
	v_lshlrev_b32_e32 v123, 16, v103
	v_and_b32_e32 v131, 0xffff0000, v103
	v_add_f32_e32 v1, 1.0, v1
	v_rcp_f32_e32 v128, v1
	v_mul_f32_e32 v1, 0xbfb8aa3b, v130
	v_exp_f32_e32 v1, v1
	v_lshlrev_b32_e32 v137, 16, v126
	v_mov_b32_e32 v103, v16
	v_lshlrev_b32_e32 v126, 16, v125
	v_add_f32_e32 v1, 1.0, v1
	v_rcp_f32_e32 v132, v1
	v_mul_f32_e32 v1, 0xbfb8aa3b, v123
	v_exp_f32_e32 v1, v1
	v_mov_b32_e32 v16, v15
	v_mov_b32_e32 v102, v14
	v_and_b32_e32 v134, 0xffff0000, v124
	v_add_f32_e32 v1, 1.0, v1
	v_rcp_f32_e32 v129, v1
	v_mul_f32_e32 v1, 0xbfb8aa3b, v131
	v_exp_f32_e32 v1, v1
	v_lshlrev_b32_e32 v136, 16, v124
	v_pk_mul_f32 v[122:123], v[128:129], v[122:123]
	v_and_b32_e32 v129, 0xffff0000, v127
	v_and_b32_e32 v128, 0xffff0000, v125
	v_lshlrev_b32_e32 v127, 16, v127
	v_pk_fma_f32 v[14:15], v[16:17], v[126:127], v[128:129]
	v_add_f32_e32 v1, 1.0, v1
	v_lshlrev_b32_e32 v126, 16, v104
	v_rcp_f32_e32 v133, v1
	v_mul_f32_e32 v1, 0xbfb8aa3b, v126
	v_exp_f32_e32 v1, v1
	v_and_b32_e32 v104, 0xffff0000, v104
	v_lshlrev_b32_e32 v127, 16, v105
	v_pk_mul_f32 v[124:125], v[132:133], v[130:131]
	v_add_f32_e32 v1, 1.0, v1
	v_rcp_f32_e32 v128, v1
	v_mul_f32_e32 v1, 0xbfb8aa3b, v104
	v_exp_f32_e32 v1, v1
	v_and_b32_e32 v105, 0xffff0000, v105
	v_pk_fma_f32 v[134:135], v[102:103], v[136:137], v[134:135]
	v_pk_mul_f32 v[124:125], v[14:15], v[124:125]
	v_add_f32_e32 v1, 1.0, v1
	v_rcp_f32_e32 v130, v1
	v_mul_f32_e32 v1, 0xbfb8aa3b, v127
	v_exp_f32_e32 v1, v1
	v_pk_mul_f32 v[122:123], v[134:135], v[122:123]
	v_and_b32_e32 v133, 0xffff0000, v100
	v_and_b32_e32 v132, 0xffff0000, v98
	v_add_f32_e32 v1, 1.0, v1
	v_rcp_f32_e32 v129, v1
	v_mul_f32_e32 v1, 0xbfb8aa3b, v105
	v_exp_f32_e32 v1, v1
	v_lshlrev_b32_e32 v135, 16, v100
	v_lshlrev_b32_e32 v134, 16, v98
	v_mov_b32_e32 v14, v6
	v_add_f32_e32 v1, 1.0, v1
	v_rcp_f32_e32 v131, v1
	v_mov_b32_e32 v15, v8
	v_pk_fma_f32 v[132:133], v[14:15], v[134:135], v[132:133]
	v_pk_mul_f32 v[126:127], v[128:129], v[126:127]
	v_and_b32_e32 v129, 0xffff0000, v101
	v_and_b32_e32 v128, 0xffff0000, v99
	v_lshlrev_b32_e32 v101, 16, v101
	v_lshlrev_b32_e32 v100, 16, v99
	v_mov_b32_e32 v8, v7
	v_pk_mul_f32 v[126:127], v[132:133], v[126:127]
	v_pk_fma_f32 v[6:7], v[8:9], v[100:101], v[128:129]
	v_pk_mul_f32 v[98:99], v[130:131], v[104:105]
	s_nop 0
	v_pk_mul_f32 v[6:7], v[6:7], v[98:99]
	s_nop 0
	v_cvt_pk_bf16_f32 v100, v126, v6
	v_cvt_pk_bf16_f32 v101, v127, v7
	v_lshlrev_b32_e32 v6, 16, v90
	v_mul_f32_e32 v1, 0xbfb8aa3b, v6
	v_exp_f32_e32 v1, v1
	v_cvt_pk_bf16_f32 v99, v123, v125
	v_cvt_pk_bf16_f32 v98, v122, v124
	v_add_f32_e32 v1, 1.0, v1
	v_and_b32_e32 v90, 0xffff0000, v90
	global_load_dwordx4 v[18:21], v[106:107], off
	global_store_dwordx4 v[120:121], v[98:101], off
	v_lshlrev_b32_e32 v7, 16, v91
	v_and_b32_e32 v91, 0xffff0000, v91
	v_rcp_f32_e32 v98, v1
	v_mul_f32_e32 v1, 0xbfb8aa3b, v90
	v_exp_f32_e32 v1, v1
	v_and_b32_e32 v105, 0xffff0000, v96
	v_lshlrev_b32_e32 v121, 16, v96
	v_lshlrev_b32_e32 v96, 16, v95
	v_add_f32_e32 v1, 1.0, v1
	v_rcp_f32_e32 v100, v1
	v_mul_f32_e32 v1, 0xbfb8aa3b, v7
	v_exp_f32_e32 v1, v1
	v_and_b32_e32 v104, 0xffff0000, v94
	v_lshlrev_b32_e32 v120, 16, v94
	v_pk_fma_f32 v[104:105], v[102:103], v[120:121], v[104:105]
	v_add_f32_e32 v1, 1.0, v1
	v_rcp_f32_e32 v99, v1
	v_mul_f32_e32 v1, 0xbfb8aa3b, v91
	v_exp_f32_e32 v1, v1
	v_pk_mul_f32 v[6:7], v[98:99], v[6:7]
	v_and_b32_e32 v99, 0xffff0000, v97
	v_add_f32_e32 v1, 1.0, v1
	v_rcp_f32_e32 v101, v1
	v_and_b32_e32 v98, 0xffff0000, v95
	v_lshlrev_b32_e32 v97, 16, v97
	v_pk_fma_f32 v[94:95], v[16:17], v[96:97], v[98:99]
	v_pk_mul_f32 v[90:91], v[100:101], v[90:91]
	v_pk_mul_f32 v[6:7], v[104:105], v[6:7]
	v_pk_mul_f32 v[90:91], v[94:95], v[90:91]
	v_lshlrev_b32_e32 v94, 16, v92
	v_mul_f32_e32 v1, 0xbfb8aa3b, v94
	v_exp_f32_e32 v1, v1
	v_and_b32_e32 v92, 0xffff0000, v92
	v_lshlrev_b32_e32 v95, 16, v93
	v_and_b32_e32 v93, 0xffff0000, v93
	v_add_f32_e32 v1, 1.0, v1
	v_rcp_f32_e32 v96, v1
	v_mul_f32_e32 v1, 0xbfb8aa3b, v92
	v_exp_f32_e32 v1, v1
	v_and_b32_e32 v101, 0xffff0000, v88
	v_lshlrev_b32_e32 v105, 16, v88
	v_lshlrev_b32_e32 v88, 16, v87
	v_add_f32_e32 v1, 1.0, v1
	v_rcp_f32_e32 v98, v1
	v_mul_f32_e32 v1, 0xbfb8aa3b, v95
	v_exp_f32_e32 v1, v1
	v_and_b32_e32 v100, 0xffff0000, v86
	v_lshlrev_b32_e32 v104, 16, v86
	v_pk_fma_f32 v[100:101], v[14:15], v[104:105], v[100:101]
	v_add_f32_e32 v1, 1.0, v1
	v_rcp_f32_e32 v97, v1
	v_mul_f32_e32 v1, 0xbfb8aa3b, v93
	v_exp_f32_e32 v1, v1
	v_pk_mul_f32 v[94:95], v[96:97], v[94:95]
	v_and_b32_e32 v97, 0xffff0000, v89
	v_add_f32_e32 v1, 1.0, v1
	v_rcp_f32_e32 v99, v1
	v_and_b32_e32 v96, 0xffff0000, v87
	v_lshlrev_b32_e32 v89, 16, v89
	v_pk_fma_f32 v[86:87], v[8:9], v[88:89], v[96:97]
	v_pk_mul_f32 v[88:89], v[98:99], v[92:93]
	v_pk_mul_f32 v[94:95], v[100:101], v[94:95]
	v_pk_mul_f32 v[86:87], v[86:87], v[88:89]
	s_nop 0
	v_cvt_pk_bf16_f32 v89, v95, v87
	v_cvt_pk_bf16_f32 v87, v7, v91
	v_cvt_pk_bf16_f32 v88, v94, v86
	v_cvt_pk_bf16_f32 v86, v6, v90
	v_lshlrev_b32_e32 v6, 16, v78
	v_mul_f32_e32 v1, 0xbfb8aa3b, v6
	v_exp_f32_e32 v1, v1
	v_and_b32_e32 v78, 0xffff0000, v78
	v_add_f32_e32 v1, 1.0, v1
	global_store_dwordx4 v[118:119], v[86:89], off
	v_lshlrev_b32_e32 v7, 16, v79
	v_and_b32_e32 v79, 0xffff0000, v79
	v_rcp_f32_e32 v86, v1
	v_mul_f32_e32 v1, 0xbfb8aa3b, v78
	v_exp_f32_e32 v1, v1
	v_and_b32_e32 v91, 0xffff0000, v84
	v_lshlrev_b32_e32 v93, 16, v84
	v_lshlrev_b32_e32 v84, 16, v83
	v_add_f32_e32 v1, 1.0, v1
	v_rcp_f32_e32 v88, v1
	v_mul_f32_e32 v1, 0xbfb8aa3b, v7
	v_exp_f32_e32 v1, v1
	v_and_b32_e32 v90, 0xffff0000, v82
	v_lshlrev_b32_e32 v92, 16, v82
	v_pk_fma_f32 v[90:91], v[102:103], v[92:93], v[90:91]
	v_add_f32_e32 v1, 1.0, v1
	v_rcp_f32_e32 v87, v1
	v_mul_f32_e32 v1, 0xbfb8aa3b, v79
	v_exp_f32_e32 v1, v1
	v_pk_mul_f32 v[6:7], v[86:87], v[6:7]
	v_and_b32_e32 v87, 0xffff0000, v85
	v_add_f32_e32 v1, 1.0, v1
	v_rcp_f32_e32 v89, v1
	v_and_b32_e32 v86, 0xffff0000, v83
	v_lshlrev_b32_e32 v85, 16, v85
	v_pk_fma_f32 v[82:83], v[16:17], v[84:85], v[86:87]
	v_pk_mul_f32 v[78:79], v[88:89], v[78:79]
	v_pk_mul_f32 v[6:7], v[90:91], v[6:7]
	v_pk_mul_f32 v[78:79], v[82:83], v[78:79]
	v_lshlrev_b32_e32 v82, 16, v80
	v_mul_f32_e32 v1, 0xbfb8aa3b, v82
	v_exp_f32_e32 v1, v1
	v_and_b32_e32 v80, 0xffff0000, v80
	v_lshlrev_b32_e32 v83, 16, v81
	v_and_b32_e32 v81, 0xffff0000, v81
	v_add_f32_e32 v1, 1.0, v1
	v_rcp_f32_e32 v84, v1
	v_mul_f32_e32 v1, 0xbfb8aa3b, v80
	v_exp_f32_e32 v1, v1
	v_and_b32_e32 v89, 0xffff0000, v76
	v_lshlrev_b32_e32 v91, 16, v76
	v_lshlrev_b32_e32 v76, 16, v75
	v_add_f32_e32 v1, 1.0, v1
	v_rcp_f32_e32 v86, v1
	v_mul_f32_e32 v1, 0xbfb8aa3b, v83
	v_exp_f32_e32 v1, v1
	v_and_b32_e32 v88, 0xffff0000, v74
	v_lshlrev_b32_e32 v90, 16, v74
	v_pk_fma_f32 v[88:89], v[14:15], v[90:91], v[88:89]
	v_add_f32_e32 v1, 1.0, v1
	v_rcp_f32_e32 v85, v1
	v_mul_f32_e32 v1, 0xbfb8aa3b, v81
	v_exp_f32_e32 v1, v1
	v_pk_mul_f32 v[82:83], v[84:85], v[82:83]
	v_and_b32_e32 v85, 0xffff0000, v77
	v_add_f32_e32 v1, 1.0, v1
	v_rcp_f32_e32 v87, v1
	v_and_b32_e32 v84, 0xffff0000, v75
	v_lshlrev_b32_e32 v77, 16, v77
	v_pk_fma_f32 v[74:75], v[8:9], v[76:77], v[84:85]
	v_pk_mul_f32 v[76:77], v[86:87], v[80:81]
	v_pk_mul_f32 v[82:83], v[88:89], v[82:83]
	v_pk_mul_f32 v[74:75], v[74:75], v[76:77]
	s_nop 0
	v_cvt_pk_bf16_f32 v77, v83, v75
	v_cvt_pk_bf16_f32 v75, v7, v79
	v_cvt_pk_bf16_f32 v76, v82, v74
	v_cvt_pk_bf16_f32 v74, v6, v78
	v_lshlrev_b32_e32 v6, 16, v66
	v_mul_f32_e32 v1, 0xbfb8aa3b, v6
	v_exp_f32_e32 v1, v1
	v_and_b32_e32 v66, 0xffff0000, v66
	v_add_f32_e32 v1, 1.0, v1
	global_store_dwordx4 v[116:117], v[74:77], off
	v_lshlrev_b32_e32 v7, 16, v67
	v_and_b32_e32 v67, 0xffff0000, v67
	v_rcp_f32_e32 v74, v1
	v_mul_f32_e32 v1, 0xbfb8aa3b, v66
	v_exp_f32_e32 v1, v1
	v_and_b32_e32 v79, 0xffff0000, v72
	v_lshlrev_b32_e32 v81, 16, v72
	v_lshlrev_b32_e32 v72, 16, v71
	v_add_f32_e32 v1, 1.0, v1
	v_rcp_f32_e32 v76, v1
	v_mul_f32_e32 v1, 0xbfb8aa3b, v7
	v_exp_f32_e32 v1, v1
	v_and_b32_e32 v78, 0xffff0000, v70
	v_lshlrev_b32_e32 v80, 16, v70
	v_pk_fma_f32 v[78:79], v[102:103], v[80:81], v[78:79]
	v_add_f32_e32 v1, 1.0, v1
	v_rcp_f32_e32 v75, v1
	v_mul_f32_e32 v1, 0xbfb8aa3b, v67
	v_exp_f32_e32 v1, v1
	v_pk_mul_f32 v[6:7], v[74:75], v[6:7]
	v_and_b32_e32 v75, 0xffff0000, v73
	v_add_f32_e32 v1, 1.0, v1
	v_rcp_f32_e32 v77, v1
	v_and_b32_e32 v74, 0xffff0000, v71
	v_lshlrev_b32_e32 v73, 16, v73
	v_pk_fma_f32 v[70:71], v[16:17], v[72:73], v[74:75]
	v_pk_mul_f32 v[66:67], v[76:77], v[66:67]
	v_pk_mul_f32 v[6:7], v[78:79], v[6:7]
	v_pk_mul_f32 v[66:67], v[70:71], v[66:67]
	v_lshlrev_b32_e32 v70, 16, v68
	v_mul_f32_e32 v1, 0xbfb8aa3b, v70
	v_exp_f32_e32 v1, v1
	v_and_b32_e32 v68, 0xffff0000, v68
	v_lshlrev_b32_e32 v71, 16, v69
	v_and_b32_e32 v69, 0xffff0000, v69
	v_add_f32_e32 v1, 1.0, v1
	v_rcp_f32_e32 v72, v1
	v_mul_f32_e32 v1, 0xbfb8aa3b, v68
	v_exp_f32_e32 v1, v1
	v_and_b32_e32 v77, 0xffff0000, v64
	v_lshlrev_b32_e32 v79, 16, v64
	v_lshlrev_b32_e32 v64, 16, v63
	v_add_f32_e32 v1, 1.0, v1
	v_rcp_f32_e32 v74, v1
	v_mul_f32_e32 v1, 0xbfb8aa3b, v71
	v_exp_f32_e32 v1, v1
	v_and_b32_e32 v76, 0xffff0000, v62
	v_lshlrev_b32_e32 v78, 16, v62
	v_pk_fma_f32 v[76:77], v[14:15], v[78:79], v[76:77]
	v_add_f32_e32 v1, 1.0, v1
	v_rcp_f32_e32 v73, v1
	v_mul_f32_e32 v1, 0xbfb8aa3b, v69
	v_exp_f32_e32 v1, v1
	v_pk_mul_f32 v[70:71], v[72:73], v[70:71]
	v_and_b32_e32 v73, 0xffff0000, v65
	v_add_f32_e32 v1, 1.0, v1
	v_rcp_f32_e32 v75, v1
	v_and_b32_e32 v72, 0xffff0000, v63
	v_lshlrev_b32_e32 v65, 16, v65
	v_pk_fma_f32 v[62:63], v[8:9], v[64:65], v[72:73]
	v_pk_mul_f32 v[64:65], v[74:75], v[68:69]
	v_pk_mul_f32 v[70:71], v[76:77], v[70:71]
	v_pk_mul_f32 v[62:63], v[62:63], v[64:65]
	s_nop 0
	v_cvt_pk_bf16_f32 v65, v71, v63
	v_cvt_pk_bf16_f32 v63, v7, v67
	v_cvt_pk_bf16_f32 v64, v70, v62
	v_cvt_pk_bf16_f32 v62, v6, v66
	v_lshlrev_b32_e32 v6, 16, v54
	v_mul_f32_e32 v1, 0xbfb8aa3b, v6
	v_exp_f32_e32 v1, v1
	v_and_b32_e32 v54, 0xffff0000, v54
	v_add_f32_e32 v1, 1.0, v1
	global_store_dwordx4 v[114:115], v[62:65], off
	v_lshlrev_b32_e32 v7, 16, v55
	v_and_b32_e32 v55, 0xffff0000, v55
	v_rcp_f32_e32 v62, v1
	v_mul_f32_e32 v1, 0xbfb8aa3b, v54
	v_exp_f32_e32 v1, v1
	v_and_b32_e32 v67, 0xffff0000, v60
	v_lshlrev_b32_e32 v69, 16, v60
	v_lshlrev_b32_e32 v60, 16, v59
	v_add_f32_e32 v1, 1.0, v1
	v_rcp_f32_e32 v64, v1
	v_mul_f32_e32 v1, 0xbfb8aa3b, v7
	v_exp_f32_e32 v1, v1
	v_and_b32_e32 v66, 0xffff0000, v58
	v_lshlrev_b32_e32 v68, 16, v58
	v_pk_fma_f32 v[66:67], v[102:103], v[68:69], v[66:67]
	v_add_f32_e32 v1, 1.0, v1
	v_rcp_f32_e32 v63, v1
	v_mul_f32_e32 v1, 0xbfb8aa3b, v55
	v_exp_f32_e32 v1, v1
	v_pk_mul_f32 v[6:7], v[62:63], v[6:7]
	v_and_b32_e32 v63, 0xffff0000, v61
	v_add_f32_e32 v1, 1.0, v1
	v_rcp_f32_e32 v65, v1
	v_and_b32_e32 v62, 0xffff0000, v59
	v_lshlrev_b32_e32 v61, 16, v61
	v_pk_fma_f32 v[58:59], v[16:17], v[60:61], v[62:63]
	v_pk_mul_f32 v[54:55], v[64:65], v[54:55]
	v_pk_mul_f32 v[6:7], v[66:67], v[6:7]
	v_pk_mul_f32 v[54:55], v[58:59], v[54:55]
	v_lshlrev_b32_e32 v58, 16, v56
	v_mul_f32_e32 v1, 0xbfb8aa3b, v58
	v_exp_f32_e32 v1, v1
	v_and_b32_e32 v56, 0xffff0000, v56
	v_lshlrev_b32_e32 v59, 16, v57
	v_and_b32_e32 v57, 0xffff0000, v57
	v_add_f32_e32 v1, 1.0, v1
	v_rcp_f32_e32 v60, v1
	v_mul_f32_e32 v1, 0xbfb8aa3b, v56
	v_exp_f32_e32 v1, v1
	v_and_b32_e32 v65, 0xffff0000, v52
	v_lshlrev_b32_e32 v67, 16, v52
	v_lshlrev_b32_e32 v52, 16, v51
	v_add_f32_e32 v1, 1.0, v1
	v_rcp_f32_e32 v62, v1
	v_mul_f32_e32 v1, 0xbfb8aa3b, v59
	v_exp_f32_e32 v1, v1
	v_and_b32_e32 v64, 0xffff0000, v50
	v_lshlrev_b32_e32 v66, 16, v50
	v_pk_fma_f32 v[64:65], v[14:15], v[66:67], v[64:65]
	v_add_f32_e32 v1, 1.0, v1
	v_rcp_f32_e32 v61, v1
	v_mul_f32_e32 v1, 0xbfb8aa3b, v57
	v_exp_f32_e32 v1, v1
	v_pk_mul_f32 v[58:59], v[60:61], v[58:59]
	v_and_b32_e32 v61, 0xffff0000, v53
	v_add_f32_e32 v1, 1.0, v1
	v_rcp_f32_e32 v63, v1
	v_and_b32_e32 v60, 0xffff0000, v51
	v_lshlrev_b32_e32 v53, 16, v53
	v_pk_fma_f32 v[50:51], v[8:9], v[52:53], v[60:61]
	v_pk_mul_f32 v[52:53], v[62:63], v[56:57]
	v_pk_mul_f32 v[58:59], v[64:65], v[58:59]
	v_pk_mul_f32 v[50:51], v[50:51], v[52:53]
	s_nop 0
	v_cvt_pk_bf16_f32 v53, v59, v51
	v_cvt_pk_bf16_f32 v51, v7, v55
	v_cvt_pk_bf16_f32 v52, v58, v50
	v_cvt_pk_bf16_f32 v50, v6, v54
	v_lshlrev_b32_e32 v6, 16, v42
	v_mul_f32_e32 v1, 0xbfb8aa3b, v6
	v_exp_f32_e32 v1, v1
	v_and_b32_e32 v42, 0xffff0000, v42
	v_add_f32_e32 v1, 1.0, v1
	global_store_dwordx4 v[112:113], v[50:53], off
	v_lshlrev_b32_e32 v7, 16, v43
	v_and_b32_e32 v43, 0xffff0000, v43
	v_rcp_f32_e32 v50, v1
	v_mul_f32_e32 v1, 0xbfb8aa3b, v42
	v_exp_f32_e32 v1, v1
	v_and_b32_e32 v55, 0xffff0000, v48
	v_lshlrev_b32_e32 v57, 16, v48
	v_lshlrev_b32_e32 v48, 16, v47
	v_add_f32_e32 v1, 1.0, v1
	v_rcp_f32_e32 v52, v1
	v_mul_f32_e32 v1, 0xbfb8aa3b, v7
	v_exp_f32_e32 v1, v1
	v_and_b32_e32 v54, 0xffff0000, v46
	v_lshlrev_b32_e32 v56, 16, v46
	v_pk_fma_f32 v[54:55], v[102:103], v[56:57], v[54:55]
	v_add_f32_e32 v1, 1.0, v1
	v_rcp_f32_e32 v51, v1
	v_mul_f32_e32 v1, 0xbfb8aa3b, v43
	v_exp_f32_e32 v1, v1
	v_pk_mul_f32 v[6:7], v[50:51], v[6:7]
	v_and_b32_e32 v51, 0xffff0000, v49
	v_add_f32_e32 v1, 1.0, v1
	v_rcp_f32_e32 v53, v1
	v_and_b32_e32 v50, 0xffff0000, v47
	v_lshlrev_b32_e32 v49, 16, v49
	v_pk_fma_f32 v[46:47], v[16:17], v[48:49], v[50:51]
	v_pk_mul_f32 v[42:43], v[52:53], v[42:43]
	v_pk_mul_f32 v[6:7], v[54:55], v[6:7]
	v_pk_mul_f32 v[42:43], v[46:47], v[42:43]
	v_lshlrev_b32_e32 v46, 16, v44
	v_mul_f32_e32 v1, 0xbfb8aa3b, v46
	v_exp_f32_e32 v1, v1
	v_and_b32_e32 v44, 0xffff0000, v44
	v_lshlrev_b32_e32 v47, 16, v45
	v_and_b32_e32 v45, 0xffff0000, v45
	v_add_f32_e32 v1, 1.0, v1
	v_rcp_f32_e32 v48, v1
	v_mul_f32_e32 v1, 0xbfb8aa3b, v44
	v_exp_f32_e32 v1, v1
	v_and_b32_e32 v53, 0xffff0000, v40
	v_lshlrev_b32_e32 v55, 16, v40
	v_lshlrev_b32_e32 v40, 16, v39
	v_add_f32_e32 v1, 1.0, v1
	v_rcp_f32_e32 v50, v1
	v_mul_f32_e32 v1, 0xbfb8aa3b, v47
	v_exp_f32_e32 v1, v1
	v_and_b32_e32 v52, 0xffff0000, v38
	v_lshlrev_b32_e32 v54, 16, v38
	v_pk_fma_f32 v[52:53], v[14:15], v[54:55], v[52:53]
	v_add_f32_e32 v1, 1.0, v1
	v_rcp_f32_e32 v49, v1
	v_mul_f32_e32 v1, 0xbfb8aa3b, v45
	v_exp_f32_e32 v1, v1
	v_pk_mul_f32 v[46:47], v[48:49], v[46:47]
	v_and_b32_e32 v49, 0xffff0000, v41
	v_add_f32_e32 v1, 1.0, v1
	v_rcp_f32_e32 v51, v1
	v_and_b32_e32 v48, 0xffff0000, v39
	v_lshlrev_b32_e32 v41, 16, v41
	v_pk_fma_f32 v[38:39], v[8:9], v[40:41], v[48:49]
	v_pk_mul_f32 v[40:41], v[50:51], v[44:45]
	v_pk_mul_f32 v[46:47], v[52:53], v[46:47]
	v_pk_mul_f32 v[38:39], v[38:39], v[40:41]
	s_nop 0
	v_cvt_pk_bf16_f32 v41, v47, v39
	v_cvt_pk_bf16_f32 v39, v7, v43
	v_cvt_pk_bf16_f32 v40, v46, v38
	v_cvt_pk_bf16_f32 v38, v6, v42
	v_lshlrev_b32_e32 v6, 16, v30
	v_mul_f32_e32 v1, 0xbfb8aa3b, v6
	v_exp_f32_e32 v1, v1
	v_and_b32_e32 v30, 0xffff0000, v30
	v_add_f32_e32 v1, 1.0, v1
	global_store_dwordx4 v[110:111], v[38:41], off
	v_lshlrev_b32_e32 v7, 16, v31
	v_and_b32_e32 v31, 0xffff0000, v31
	v_rcp_f32_e32 v38, v1
	v_mul_f32_e32 v1, 0xbfb8aa3b, v30
	v_exp_f32_e32 v1, v1
	v_and_b32_e32 v43, 0xffff0000, v36
	v_lshlrev_b32_e32 v45, 16, v36
	v_lshlrev_b32_e32 v36, 16, v35
	v_add_f32_e32 v1, 1.0, v1
	v_rcp_f32_e32 v40, v1
	v_mul_f32_e32 v1, 0xbfb8aa3b, v7
	v_exp_f32_e32 v1, v1
	v_and_b32_e32 v42, 0xffff0000, v34
	v_lshlrev_b32_e32 v44, 16, v34
	v_pk_fma_f32 v[42:43], v[102:103], v[44:45], v[42:43]
	v_add_f32_e32 v1, 1.0, v1
	v_rcp_f32_e32 v39, v1
	v_mul_f32_e32 v1, 0xbfb8aa3b, v31
	v_exp_f32_e32 v1, v1
	v_pk_mul_f32 v[6:7], v[38:39], v[6:7]
	v_and_b32_e32 v39, 0xffff0000, v37
	v_add_f32_e32 v1, 1.0, v1
	v_rcp_f32_e32 v41, v1
	v_and_b32_e32 v38, 0xffff0000, v35
	v_lshlrev_b32_e32 v37, 16, v37
	v_pk_fma_f32 v[34:35], v[16:17], v[36:37], v[38:39]
	v_pk_mul_f32 v[30:31], v[40:41], v[30:31]
	v_pk_mul_f32 v[6:7], v[42:43], v[6:7]
	v_pk_mul_f32 v[30:31], v[34:35], v[30:31]
	v_lshlrev_b32_e32 v34, 16, v32
	v_mul_f32_e32 v1, 0xbfb8aa3b, v34
	v_exp_f32_e32 v1, v1
	v_and_b32_e32 v32, 0xffff0000, v32
	v_lshlrev_b32_e32 v35, 16, v33
	v_and_b32_e32 v33, 0xffff0000, v33
	v_add_f32_e32 v1, 1.0, v1
	v_rcp_f32_e32 v36, v1
	v_mul_f32_e32 v1, 0xbfb8aa3b, v32
	v_exp_f32_e32 v1, v1
	v_and_b32_e32 v41, 0xffff0000, v28
	v_lshlrev_b32_e32 v43, 16, v28
	v_lshlrev_b32_e32 v28, 16, v27
	v_add_f32_e32 v1, 1.0, v1
	v_rcp_f32_e32 v38, v1
	v_mul_f32_e32 v1, 0xbfb8aa3b, v35
	v_exp_f32_e32 v1, v1
	v_and_b32_e32 v40, 0xffff0000, v26
	v_lshlrev_b32_e32 v42, 16, v26
	v_pk_fma_f32 v[40:41], v[14:15], v[42:43], v[40:41]
	v_add_f32_e32 v1, 1.0, v1
	v_rcp_f32_e32 v37, v1
	v_mul_f32_e32 v1, 0xbfb8aa3b, v33
	v_exp_f32_e32 v1, v1
	v_pk_mul_f32 v[34:35], v[36:37], v[34:35]
	v_and_b32_e32 v37, 0xffff0000, v29
	v_add_f32_e32 v1, 1.0, v1
	v_rcp_f32_e32 v39, v1
	v_and_b32_e32 v36, 0xffff0000, v27
	v_lshlrev_b32_e32 v29, 16, v29
	v_pk_fma_f32 v[26:27], v[8:9], v[28:29], v[36:37]
	v_pk_mul_f32 v[28:29], v[38:39], v[32:33]
	v_pk_mul_f32 v[34:35], v[40:41], v[34:35]
	v_pk_mul_f32 v[26:27], v[26:27], v[28:29]
	s_nop 0
	v_cvt_pk_bf16_f32 v29, v35, v27
	v_cvt_pk_bf16_f32 v27, v7, v31
	v_cvt_pk_bf16_f32 v28, v34, v26
	v_cvt_pk_bf16_f32 v26, v6, v30
	s_waitcnt vmcnt(6)
	v_lshlrev_b32_e32 v6, 16, v18
	v_mul_f32_e32 v1, 0xbfb8aa3b, v6
	v_exp_f32_e32 v1, v1
	v_and_b32_e32 v18, 0xffff0000, v18
	v_add_f32_e32 v1, 1.0, v1
	global_store_dwordx4 v[108:109], v[26:29], off
	v_lshlrev_b32_e32 v7, 16, v19
	v_and_b32_e32 v19, 0xffff0000, v19
	v_rcp_f32_e32 v26, v1
	v_mul_f32_e32 v1, 0xbfb8aa3b, v18
	v_exp_f32_e32 v1, v1
	v_and_b32_e32 v31, 0xffff0000, v24
	v_lshlrev_b32_e32 v33, 16, v24
	v_lshlrev_b32_e32 v24, 16, v23
	v_add_f32_e32 v1, 1.0, v1
	v_rcp_f32_e32 v28, v1
	v_mul_f32_e32 v1, 0xbfb8aa3b, v7
	v_exp_f32_e32 v1, v1
	v_and_b32_e32 v30, 0xffff0000, v22
	v_lshlrev_b32_e32 v32, 16, v22
	v_pk_fma_f32 v[30:31], v[102:103], v[32:33], v[30:31]
	v_add_f32_e32 v1, 1.0, v1
	v_rcp_f32_e32 v27, v1
	v_mul_f32_e32 v1, 0xbfb8aa3b, v19
	v_exp_f32_e32 v1, v1
	v_pk_mul_f32 v[6:7], v[26:27], v[6:7]
	v_and_b32_e32 v27, 0xffff0000, v25
	v_add_f32_e32 v1, 1.0, v1
	v_rcp_f32_e32 v29, v1
	v_and_b32_e32 v26, 0xffff0000, v23
	v_lshlrev_b32_e32 v25, 16, v25
	v_pk_fma_f32 v[16:17], v[16:17], v[24:25], v[26:27]
	v_pk_mul_f32 v[18:19], v[28:29], v[18:19]
	v_and_b32_e32 v27, 0xffff0000, v12
	v_pk_mul_f32 v[16:17], v[16:17], v[18:19]
	v_lshlrev_b32_e32 v18, 16, v20
	v_mul_f32_e32 v1, 0xbfb8aa3b, v18
	v_exp_f32_e32 v1, v1
	v_and_b32_e32 v20, 0xffff0000, v20
	v_lshlrev_b32_e32 v19, 16, v21
	v_and_b32_e32 v21, 0xffff0000, v21
	v_add_f32_e32 v1, 1.0, v1
	v_rcp_f32_e32 v22, v1
	v_mul_f32_e32 v1, 0xbfb8aa3b, v20
	v_exp_f32_e32 v1, v1
	v_and_b32_e32 v26, 0xffff0000, v10
	v_lshlrev_b32_e32 v29, 16, v12
	v_lshlrev_b32_e32 v28, 16, v10
	v_add_f32_e32 v1, 1.0, v1
	v_rcp_f32_e32 v24, v1
	v_mul_f32_e32 v1, 0xbfb8aa3b, v19
	v_exp_f32_e32 v1, v1
	v_pk_fma_f32 v[14:15], v[14:15], v[28:29], v[26:27]
	v_lshlrev_b32_e32 v12, 16, v11
	v_pk_mul_f32 v[6:7], v[30:31], v[6:7]
	v_add_f32_e32 v1, 1.0, v1
	v_rcp_f32_e32 v23, v1
	v_mul_f32_e32 v1, 0xbfb8aa3b, v21
	v_exp_f32_e32 v1, v1
	v_pk_mul_f32 v[18:19], v[22:23], v[18:19]
	s_nop 0
	v_pk_mul_f32 v[14:15], v[14:15], v[18:19]
	v_add_f32_e32 v1, 1.0, v1
	v_rcp_f32_e32 v25, v1
	v_and_b32_e32 v19, 0xffff0000, v13
	v_and_b32_e32 v18, 0xffff0000, v11
	v_lshlrev_b32_e32 v13, 16, v13
	v_pk_fma_f32 v[8:9], v[8:9], v[12:13], v[18:19]
	v_pk_mul_f32 v[10:11], v[24:25], v[20:21]
	s_nop 0
	v_pk_mul_f32 v[8:9], v[8:9], v[10:11]
	v_cvt_pk_bf16_f32 v6, v6, v16
	v_cvt_pk_bf16_f32 v9, v15, v9
	v_cvt_pk_bf16_f32 v8, v14, v8
	v_cvt_pk_bf16_f32 v7, v7, v17
	global_store_dwordx4 v[106:107], v[6:9], off
	s_mov_b64 s[0:1], -1
	s_and_b64 vcc, exec, s[10:11]
	s_cbranch_vccnz .LBB0_393

.LBB0_484:
	v_mov_b32_e32 v1, v0
	s_mov_b64 s[8:9], s[50:51]
	v_readfirstlane_b32 s89, v1
	s_ashr_i32 s22, s89, 6
	s_add_i32 s0, s22, s90
	s_ashr_i32 s1, s0, 31
	v_readlane_b32 s36, v252, 0
	s_lshl_b64 s[0:1], s[0:1], 2
	v_readlane_b32 s38, v252, 2
	v_readlane_b32 s39, v252, 3
	s_add_u32 s4, s38, s0
	v_readlane_b32 s40, v252, 4
	s_addc_u32 s5, s39, s1
	v_readlane_b32 s41, v252, 5
	s_add_u32 s0, s40, s0
	s_addc_u32 s1, s41, s1
	global_load_dword v8, v139, s[4:5]
	global_load_dword v6, v139, s[0:1]
	v_and_b32_e32 v137, 63, v1
	v_readlane_b32 s0, v250, 47
	v_readlane_b32 s1, v250, 48
	s_ashr_i32 s23, s22, 31
	v_or_b32_e32 v12, s88, v137
	v_ashrrev_i32_e32 v13, 31, v12
	v_lshlrev_b64 v[12:13], 7, v[12:13]
	v_lshl_add_u64 v[12:13], s[0:1], 0, v[12:13]
	v_lshl_add_u64 v[12:13], s[22:23], 2, v[12:13]
	global_load_dword v14, v[12:13], off
	v_and_b32_e32 v136, 64, v228
	v_cmp_eq_u32_e64 s[38:39], 0, v137
	v_readlane_b32 s37, v252, 1
	v_cmp_gt_u32_e64 s[36:37], 16, v137
	v_and_b32_e32 v122, 0x7f, v1
	v_writelane_b32 v253, s84, 51
	v_lshlrev_b32_e32 v138, 3, v122
	v_readlane_b32 s42, v252, 6
	v_readlane_b32 s43, v252, 7
	v_readlane_b32 s44, v252, 8
	v_readlane_b32 s45, v252, 9
	v_readlane_b32 s46, v252, 10
	v_readlane_b32 s47, v252, 11
	v_readlane_b32 s48, v252, 12
	v_readlane_b32 s49, v252, 13
	v_readlane_b32 s50, v252, 14
	v_readlane_b32 s51, v252, 15
	s_waitcnt vmcnt(0)
	v_mul_f32_e32 v7, 0x3fb8aa3b, v6
	v_fma_f32 v9, v6, s80, -v7
	v_rndne_f32_e32 v10, v7
	v_fmac_f32_e32 v9, 0x32a5705f, v6
	v_sub_f32_e32 v7, v7, v10
	v_add_f32_e32 v7, v7, v9
	v_exp_f32_e32 v7, v7
	v_cvt_i32_f32_e32 v9, v10
	v_cmp_ngt_f32_e32 vcc, s81, v6
	v_ldexp_f32 v7, v7, v9
	s_nop 0
	v_cndmask_b32_e32 v7, 0, v7, vcc
	v_cmp_nlt_f32_e32 vcc, s82, v6
	s_nop 0
	s_nop 0
	v_cndmask_b32_e32 v9, v231, v7, vcc
	v_cmp_lt_u32_e64 s[0:1], 63, v122
	s_waitcnt vmcnt(0)
	v_add_f32_e32 v6, v8, v14
	v_max_f32_e32 v7, 0, v6
	v_mul_f32_e64 v6, |v6|, s13
	v_exp_f32_e32 v6, v6
	v_add_u32_e32 v8, -1, v228
	v_cmp_lt_i32_e32 vcc, v8, v136
	v_add_f32_e32 v6, 1.0, v6
	v_log_f32_e32 v6, v6
	v_cndmask_b32_e32 v8, v8, v228, vcc
	v_lshlrev_b32_e32 v8, 2, v8
	v_fmac_f32_e32 v7, 0x3f317218, v6
	v_mul_f32_e64 v6, v7, -v9
	ds_bpermute_b32 v8, v8, v6
	s_waitcnt lgkmcnt(0)
	v_fma_f32 v8, v7, -v9, v8
	v_cndmask_b32_e64 v6, v8, v6, s[38:39]
	v_add_u32_e32 v8, -2, v228
	v_cmp_lt_i32_e32 vcc, v8, v136
	s_nop 1
	v_cndmask_b32_e32 v8, v8, v228, vcc
	v_lshlrev_b32_e32 v8, 2, v8
	ds_bpermute_b32 v8, v8, v6
	v_cmp_gt_u32_e32 vcc, 2, v137
	s_waitcnt lgkmcnt(0)
	v_add_f32_e32 v8, v6, v8
	v_cndmask_b32_e32 v6, v8, v6, vcc
	v_add_u32_e32 v8, -4, v228
	v_cmp_lt_i32_e32 vcc, v8, v136
	s_nop 1
	v_cndmask_b32_e32 v8, v8, v228, vcc
	v_lshlrev_b32_e32 v8, 2, v8
	ds_bpermute_b32 v8, v8, v6
	v_cmp_gt_u32_e32 vcc, 4, v137
	s_waitcnt lgkmcnt(0)
	v_add_f32_e32 v8, v6, v8
	v_cndmask_b32_e32 v6, v8, v6, vcc
	v_add_u32_e32 v8, -8, v228
	v_cmp_lt_i32_e32 vcc, v8, v136
	s_nop 1
	v_cndmask_b32_e32 v8, v8, v228, vcc
	v_lshlrev_b32_e32 v8, 2, v8
	ds_bpermute_b32 v8, v8, v6
	v_cmp_gt_u32_e32 vcc, 8, v137
	s_waitcnt lgkmcnt(0)
	v_add_f32_e32 v8, v6, v8
	v_cndmask_b32_e32 v6, v8, v6, vcc
	v_add_u32_e32 v8, -16, v228
	v_cmp_lt_i32_e32 vcc, v8, v136
	s_nop 1
	v_cndmask_b32_e32 v8, v8, v228, vcc
	v_lshlrev_b32_e32 v8, 2, v8
	ds_bpermute_b32 v8, v8, v6
	s_waitcnt lgkmcnt(0)
	v_add_f32_e32 v8, v6, v8
	v_cndmask_b32_e64 v6, v8, v6, s[36:37]
	v_subrev_u32_e32 v8, 32, v228
	v_cmp_lt_i32_e32 vcc, v8, v136
	s_nop 1
	v_cndmask_b32_e32 v8, v8, v228, vcc
	v_lshlrev_b32_e32 v8, 2, v8
	ds_bpermute_b32 v8, v8, v6
	v_cmp_gt_u32_e32 vcc, 32, v137
	s_waitcnt lgkmcnt(0)
	v_add_f32_e32 v8, v6, v8
	v_cndmask_b32_e32 v6, v8, v6, vcc
	v_lshl_add_u32 v8, v137, 3, s22
	v_lshl_add_u32 v8, v8, 2, 0
	v_add_u32_e32 v9, 0x21800, v8
	s_barrier
	ds_write_b32 v9, v7
	v_add_u32_e32 v7, 0x22000, v8
	v_cmp_gt_u32_e32 vcc, 64, v122
	ds_write_b32 v7, v6
	s_waitcnt lgkmcnt(0)
	s_barrier
	s_and_saveexec_b64 s[4:5], vcc
	s_xor_b64 s[30:31], exec, s[4:5]
	v_lshlrev_b32_e32 v138, 3, v122
	v_add_u32_e32 v46, 0x1100, v138
	v_lshl_add_u32 v146, v122, 4, 0
	s_or_saveexec_b64 s[30:31], s[30:31]
	v_mov_b32_e32 v147, 0x208
	s_mov_b64 s[14:15], 0x1000
	s_mov_b64 s[42:43], 0x60
	s_mov_b64 s[50:51], s[8:9]
	s_xor_b64 exec, exec, s[30:31]
	s_cbranch_execz .LBB0_492
	s_movk_i32 s4, 0x5f
	v_cmp_lt_u32_e32 vcc, s4, v122
	s_and_saveexec_b64 s[4:5], vcc
	s_xor_b64 s[34:35], exec, s[4:5]
	s_add_i32 s4, 0, 0x10400
	v_lshl_add_u32 v6, v138, 1, s4
	v_add_u32_e32 v46, 0xb00, v138
	v_add_u32_e32 v146, 0xfffffa00, v6
	s_andn2_saveexec_b64 s[34:35], s[34:35]
	s_cbranch_execz .LBB0_491
	v_readlane_b32 s4, v253, 7
	v_add_u32_e32 v46, 0x1100, v138
	s_nop 0
	v_lshl_add_u32 v6, v138, 1, s4
	v_add_u32_e32 v146, 0xfffffc00, v6
